# chunk attention + cross attention loops: packed f32 VOP3P ops (v_pk_mul/v_pk_fma beside MFMAs) split into their two scalar halves (bit-identical)
# baseline (speedup 1.0000x reference)
; DI unsigned pack2(float a, float b) { const f32x2 v = {a, b}; return __builtin_bit_cast(unsigned, __builtin_convertvector(v, bf16v2)); }
; DI void attn_item(const Params& p, char* lds, int item) {
;     ...
;   const float inv = __builtin_amdgcn_rcpf(lrun + __shfl_xor(lrun, 32));
; #pragma unroll
;   for (int dt = 0; dt < 2; ++dt)
; #pragma unroll
;     for (int g = 0; g < 4; ++g) {
;       uint2 o; o.x = pack2(O[dt][4 * g] * inv, O[dt][4 * g + 1] * inv); o.y = pack2(O[dt][4 * g + 2] * inv, O[dt][4 * g + 3] * inv);
;       *(uint2*)(MIX + (q0 + l31) * 1024 + h * 64 + dt * 32 + 8 * g + 4 * hh) = o;
;     }
.LBB0_345:
	s_waitcnt vmcnt(1)
	v_and_b32_e32 v2, 64, v114
	v_xor_b32_e32 v0, 32, v114
	v_add_u32_e32 v2, 64, v2
	v_cmp_lt_i32_e32 vcc, v0, v2
	v_lshl_add_u64 v[2:3], s[4:5], 0, v[84:85]
	s_lshl_b32 s10, s9, 1
	v_cndmask_b32_e32 v0, v114, v0, vcc
	v_lshlrev_b32_e32 v0, 2, v0
	ds_bpermute_b32 v0, v0, v137
	v_mov_b32_e32 v87, v1
	v_lshl_add_u64 v[2:3], v[2:3], 0, s[10:11]
	v_lshl_add_u64 v[2:3], v[2:3], 0, v[86:87]
	s_add_i32 s76, s76, s2
	s_waitcnt lgkmcnt(0)
	v_add_f32_e32 v0, v137, v0
	v_rcp_f32_e32 v0, v0
	s_add_i32 s13, s13, s15
	s_cmpk_lt_i32 s76, 0x800
	v_mul_f32_e32 v4, v32, v0
	v_mul_f32_e32 v5, v33, v0
	s_waitcnt vmcnt(0)
	v_mul_f32_e32 v6, v34, v0
	v_mul_f32_e32 v7, v35, v0
	v_cvt_pk_bf16_f32 v4, v4, v5
	v_cvt_pk_bf16_f32 v5, v6, v7
	global_store_dwordx2 v[2:3], v[4:5], off
	v_mul_f32_e32 v4, v36, v0
	v_mul_f32_e32 v5, v37, v0
	v_mul_f32_e32 v6, v38, v0
	v_mul_f32_e32 v7, v39, v0
	v_cvt_pk_bf16_f32 v4, v4, v5
	v_cvt_pk_bf16_f32 v5, v6, v7
	global_store_dwordx2 v[2:3], v[4:5], off offset:16
	v_mul_f32_e32 v4, v40, v0
	v_mul_f32_e32 v5, v41, v0
	v_mul_f32_e32 v6, v42, v0
	v_mul_f32_e32 v7, v43, v0
	v_cvt_pk_bf16_f32 v4, v4, v5
	v_cvt_pk_bf16_f32 v5, v6, v7
	global_store_dwordx2 v[2:3], v[4:5], off offset:32
	v_mul_f32_e32 v4, v44, v0
	v_mul_f32_e32 v5, v45, v0
	v_mul_f32_e32 v6, v46, v0
	v_mul_f32_e32 v7, v47, v0
	v_cvt_pk_bf16_f32 v4, v4, v5
	v_cvt_pk_bf16_f32 v5, v6, v7
	global_store_dwordx2 v[2:3], v[4:5], off offset:48
	v_mul_f32_e32 v4, v16, v0
	v_mul_f32_e32 v5, v17, v0
	v_mul_f32_e32 v6, v18, v0
	v_mul_f32_e32 v7, v19, v0
	v_cvt_pk_bf16_f32 v4, v4, v5
	v_cvt_pk_bf16_f32 v5, v6, v7
	global_store_dwordx2 v[2:3], v[4:5], off offset:64
	v_mul_f32_e32 v4, v20, v0
	v_mul_f32_e32 v5, v21, v0
	v_mul_f32_e32 v6, v22, v0
	v_mul_f32_e32 v7, v23, v0
	v_cvt_pk_bf16_f32 v4, v4, v5
	v_cvt_pk_bf16_f32 v5, v6, v7
	global_store_dwordx2 v[2:3], v[4:5], off offset:80
	v_mul_f32_e32 v4, v24, v0
	v_mul_f32_e32 v5, v25, v0
	v_mul_f32_e32 v6, v26, v0
	v_mul_f32_e32 v7, v27, v0
	v_cvt_pk_bf16_f32 v4, v4, v5
	v_cvt_pk_bf16_f32 v5, v6, v7
	global_store_dwordx2 v[2:3], v[4:5], off offset:96
	v_mul_f32_e32 v4, v28, v0
	v_mul_f32_e32 v5, v29, v0
	v_mul_f32_e32 v6, v30, v0
	v_mul_f32_e32 v7, v31, v0
	v_cvt_pk_bf16_f32 v4, v4, v5
	v_cvt_pk_bf16_f32 v5, v6, v7
	global_store_dwordx2 v[2:3], v[4:5], off offset:112
	s_cbranch_scc0 .LBB0_375

; DI void attn_item(const Params& p, char* lds, int item) {
;     ...
;   for (int i = tid; i < 257; i += 512) biasl[i] = p.in[10][h * 257 + i] * 1.4426950408889634f;
.LBB0_350:
	v_add_u32_e32 v10, s18, v4
	v_add_u32_e32 v12, s19, v5
	v_ashrrev_i32_e32 v11, 31, v10
	v_ashrrev_i32_e32 v13, 31, v12
	v_lshl_add_u64 v[10:11], v[10:11], 2, s[40:41]
	v_lshl_add_u64 v[12:13], v[12:13], 2, s[40:41]
	global_load_dword v10, v[10:11], off
	s_nop 0
	global_load_dword v11, v[12:13], off
	v_add_u32_e32 v12, s22, v5
	v_ashrrev_i32_e32 v13, 31, v12
	v_lshl_add_u64 v[12:13], v[12:13], 2, s[40:41]
	v_add_u32_e32 v7, -4, v7
	s_add_i32 s78, s78, 8
	v_cmp_eq_u32_e32 vcc, 0, v7
	s_or_b64 s[30:31], vcc, s[30:31]
	v_mov_b32_e32 v9, s78
	s_waitcnt vmcnt(0)
	v_mul_f32_e32 v10, s12, v10
	v_mul_f32_e32 v11, s12, v11
	ds_write2st64_b32 v8, v10, v11 offset1:8
	v_add_u32_e32 v10, s23, v4
	v_ashrrev_i32_e32 v11, 31, v10
	v_lshl_add_u64 v[10:11], v[10:11], 2, s[40:41]
	global_load_dword v10, v[10:11], off
	s_nop 0
	global_load_dword v11, v[12:13], off
	v_add_u32_e32 v12, s27, v5
	v_ashrrev_i32_e32 v13, 31, v12
	v_lshl_add_u64 v[12:13], v[12:13], 2, s[40:41]
	s_waitcnt vmcnt(0)
	v_mul_f32_e32 v10, s12, v10
	v_mul_f32_e32 v11, s12, v11
	ds_write2st64_b32 v8, v10, v11 offset0:16 offset1:24
	v_add_u32_e32 v10, s26, v4
	v_ashrrev_i32_e32 v11, 31, v10
	v_lshl_add_u64 v[10:11], v[10:11], 2, s[40:41]
	global_load_dword v10, v[10:11], off
	s_nop 0
	global_load_dword v11, v[12:13], off
	v_add_u32_e32 v12, s9, v5
	v_ashrrev_i32_e32 v13, 31, v12
	v_lshl_add_u64 v[12:13], v[12:13], 2, s[40:41]
	v_add_u32_e32 v5, 0x1000, v5
	s_waitcnt vmcnt(0)
	v_mul_f32_e32 v10, s12, v10
	v_mul_f32_e32 v11, s12, v11
	ds_write2st64_b32 v8, v10, v11 offset0:32 offset1:40
	v_add_u32_e32 v10, s77, v4
	v_ashrrev_i32_e32 v11, 31, v10
	v_lshl_add_u64 v[10:11], v[10:11], 2, s[40:41]
	global_load_dword v10, v[10:11], off
	s_nop 0
	global_load_dword v11, v[12:13], off
	v_add_u32_e32 v4, 0x1000, v4
	s_waitcnt vmcnt(0)
	v_mul_f32_e32 v10, s12, v10
	v_mul_f32_e32 v11, s12, v11
	ds_write2st64_b32 v8, v10, v11 offset0:48 offset1:56
	v_add_u32_e32 v8, 0x4000, v8
	s_andn2_b64 exec, exec, s[30:31]
	s_cbranch_execnz .LBB0_350
	s_or_b64 exec, exec, s[30:31]

; DI void attn_item(const Params& p, char* lds, int item) {
;     ...
;   for (int i = tid; i < 257; i += 512) biasl[i] = p.in[10][h * 257 + i] * 1.4426950408889634f;
.LBB0_354:
	v_add_u32_e32 v8, s18, v4
	v_add_u32_e32 v10, s19, v5
	v_ashrrev_i32_e32 v9, 31, v8
	v_ashrrev_i32_e32 v11, 31, v10
	v_lshl_add_u64 v[8:9], v[8:9], 2, s[40:41]
	v_lshl_add_u64 v[10:11], v[10:11], 2, s[40:41]
	global_load_dword v8, v[8:9], off
	s_nop 0
	global_load_dword v9, v[10:11], off
	v_add_u32_e32 v3, -1, v3
	v_cmp_eq_u32_e32 vcc, 0, v3
	v_add_u32_e32 v5, 0x400, v5
	v_add_u32_e32 v4, 0x400, v4
	s_or_b64 s[22:23], vcc, s[22:23]
	s_waitcnt vmcnt(0)
	v_mul_f32_e32 v8, s12, v8
	v_mul_f32_e32 v9, s12, v9
	ds_write2st64_b32 v6, v8, v9 offset1:8
	v_add_u32_e32 v6, 0x1000, v6
	s_andn2_b64 exec, exec, s[22:23]
	s_cbranch_execnz .LBB0_354

; #define MFMA(a, b, c) __builtin_amdgcn_mfma_f32_32x32x16_bf16((a), (b), (c), 0, 0, 0)
; DI f32x16 zero16() { f32x16 z; for (int i = 0; i < 16; ++i) z[i] = 0.f; return z; }
; DI void attn_item(const Params& p, char* lds, int item) {
;     ...
;     if (kc >= qc - 8 && kc <= qc) {
;       f32x16 S[2];
;       float mx = -INFINITY;
; #pragma unroll
;       for (int sub = 0; sub < 2; ++sub) {
;         const u16* kl = Kl + cur * 64 * 72 + (sub * 32 + pi) * 72 + 8 * hh;
;         S[sub] = zero16();
; #pragma unroll
;         for (int kk = 0; kk < 4; ++kk) S[sub] = MFMA(ldfrag(kl + kk * 16), Qf[kk], S[sub]);
;         const int relbase = (kc * 64 + sub * 32 + 8 * hh) - (qc * 64 + qt * 32 + l31);
;         if ((kc * 64 + sub * 32 + 31) - (qc * 64 + qt * 32) <= -128) {
;           const float b0 = biasl[0];
; #pragma unroll
;           for (int r = 0; r < 16; ++r) { const float sv = S[sub][r] * 0.18033688011112042f + b0; S[sub][r] = sv; mx = fmaxf(mx, sv); }
;         } else {
; #pragma unroll
;           for (int r = 0; r < 16; ++r) {
;             int rel = relbase + 16 * (r >> 3) + (r & 7);
;             rel = rel < -128 ? -128 : (rel > 128 ? 128 : rel);
;             const float sv = S[sub][r] * 0.18033688011112042f + biasl[rel + 128];
;             S[sub][r] = sv; mx = fmaxf(mx, sv);
;           }
;         }
.LBB0_363:
	v_cmp_ge_i32_e32 vcc, s26, v132
	v_cmp_le_i32_e64 s[0:1], s26, v87
	s_and_b32 s10, s26, 1
	s_and_b64 s[16:17], vcc, s[0:1]
	s_and_saveexec_b64 s[0:1], s[16:17]
	s_cbranch_execz .LBB0_373
	s_mul_i32 s30, s10, 0x2400
	v_add_u32_e32 v0, s30, v134
	ds_read_b128 v[10:13], v0
	ds_read_b128 v[88:91], v0 offset:32
	v_add_u32_e32 v98, s22, v136
	v_cmp_lt_i32_e32 vcc, s42, v98
	s_waitcnt vmcnt(3) lgkmcnt(1)
	v_mfma_f32_32x32x16_bf16 v[48:63], v[10:13], v[64:67], 0
	s_waitcnt vmcnt(2) lgkmcnt(0)
	v_mfma_f32_32x32x16_bf16 v[48:63], v[88:91], v[68:71], v[48:63]
	ds_read_b128 v[10:13], v0 offset:64
	ds_read_b128 v[88:91], v0 offset:96
	s_waitcnt vmcnt(1) lgkmcnt(1)
	v_mfma_f32_32x32x16_bf16 v[48:63], v[10:13], v[72:75], v[48:63]
	s_waitcnt vmcnt(0) lgkmcnt(0)
	v_mfma_f32_32x32x16_bf16 v[48:63], v[88:91], v[76:79], v[48:63]
	s_and_saveexec_b64 s[16:17], vcc
	s_xor_b64 s[16:17], exec, s[16:17]
	s_cbranch_execz .LBB0_366
	v_add_u32_e32 v94, s22, v135
	v_med3_i32 v10, v94, s43, v115
	v_med3_i32 v11, v94, s48, v116
	v_med3_i32 v12, v94, s50, v117
	v_med3_i32 v13, v94, s51, v118
	v_med3_i32 v14, v94, s54, v119
	v_med3_i32 v15, v94, s55, v120
	v_lshl_add_u32 v10, v10, 2, 0
	v_lshl_add_u32 v11, v11, 2, 0
	v_lshl_add_u32 v12, v12, 2, 0
	v_lshl_add_u32 v13, v13, 2, 0
	v_lshl_add_u32 v14, v14, 2, 0
	v_lshl_add_u32 v15, v15, 2, 0
	v_med3_i32 v88, v94, s56, v121
	v_med3_i32 v89, v94, s57, v122
	v_lshl_add_u32 v88, v88, 2, 0
	v_lshl_add_u32 v89, v89, 2, 0
	ds_read_b32 v10, v10 offset:37376
	ds_read_b32 v11, v11 offset:37380
	ds_read_b32 v12, v12 offset:37384
	ds_read_b32 v13, v13 offset:37388
	ds_read_b32 v14, v14 offset:37392
	ds_read_b32 v15, v15 offset:37396
	ds_read_b32 v90, v88 offset:37400
	ds_read_b32 v91, v89 offset:37404
	s_waitcnt lgkmcnt(6)
	v_fma_f32 v92, v48, s14, v10
	v_fma_f32 v93, v49, s14, v11
	s_waitcnt lgkmcnt(4)
	v_fma_f32 v88, v50, s14, v12
	v_fma_f32 v89, v51, s14, v13
	v_max3_f32 v10, v92, s49, v93
	v_max3_f32 v10, v10, v88, v89
	s_waitcnt lgkmcnt(2)
	v_fma_f32 v12, v52, s14, v14
	v_fma_f32 v13, v53, s14, v15
	v_med3_i32 v15, v94, s59, v124
	v_max3_f32 v14, v10, v12, v13
	s_waitcnt lgkmcnt(0)
	v_fma_f32 v10, v54, s14, v90
	v_fma_f32 v11, v55, s14, v91
	v_med3_i32 v48, v94, s60, v125
	v_max3_f32 v54, v14, v10, v11
	v_med3_i32 v14, v94, s58, v123
	v_med3_i32 v49, v94, s61, v126
	v_med3_i32 v50, v94, s72, v127
	v_med3_i32 v51, v94, s73, v128
	v_med3_i32 v52, v94, s74, v129
	v_med3_i32 v53, v94, s75, v130
	v_lshl_add_u32 v14, v14, 2, 0
	v_lshl_add_u32 v15, v15, 2, 0
	v_lshl_add_u32 v48, v48, 2, 0
	v_lshl_add_u32 v49, v49, 2, 0
	v_lshl_add_u32 v50, v50, 2, 0
	v_lshl_add_u32 v51, v51, 2, 0
	v_lshl_add_u32 v52, v52, 2, 0
	v_lshl_add_u32 v53, v53, 2, 0
	ds_read_b32 v14, v14 offset:37440
	ds_read_b32 v15, v15 offset:37444
	ds_read_b32 v48, v48 offset:37448
	ds_read_b32 v49, v49 offset:37452
	ds_read_b32 v50, v50 offset:37456
	ds_read_b32 v51, v51 offset:37460
	ds_read_b32 v52, v52 offset:37464
	ds_read_b32 v53, v53 offset:37468
	s_waitcnt lgkmcnt(6)
	v_fma_f32 v96, v56, s14, v14
	v_fma_f32 v97, v57, s14, v15
	s_waitcnt lgkmcnt(4)
	v_fma_f32 v94, v58, s14, v48
	v_fma_f32 v95, v59, s14, v49
	v_max3_f32 v14, v54, v96, v97
	v_max3_f32 v14, v14, v94, v95
	s_waitcnt lgkmcnt(2)
	v_fma_f32 v90, v60, s14, v50
	v_fma_f32 v91, v61, s14, v51
	s_nop 0
	v_max3_f32 v48, v14, v90, v91
	s_waitcnt lgkmcnt(0)
	v_fma_f32 v14, v62, s14, v52
	v_fma_f32 v15, v63, s14, v53
	s_nop 0
	v_max3_f32 v139, v48, v14, v15
.LBB0_366:
	s_andn2_saveexec_b64 s[16:17], s[16:17]
	s_cbranch_execz .LBB0_368
	ds_read_b32 v14, v1 offset:36864
	s_waitcnt lgkmcnt(0)
	s_nop 4
	v_fma_f32 v92, v48, s14, v14
	v_fma_f32 v93, v49, s14, v14
	v_fma_f32 v88, v50, s14, v14
	v_fma_f32 v89, v51, s14, v14
	v_fma_f32 v12, v52, s14, v14
	v_fma_f32 v13, v53, s14, v14
	v_fma_f32 v10, v54, s14, v14
	v_fma_f32 v11, v55, s14, v14
	v_fma_f32 v96, v56, s14, v14
	v_fma_f32 v97, v57, s14, v14
	v_max3_f32 v15, v92, s49, v93
	v_max3_f32 v15, v15, v88, v89
	v_max3_f32 v15, v15, v12, v13
	v_max3_f32 v15, v15, v10, v11
	v_max3_f32 v15, v15, v96, v97
	v_fma_f32 v94, v58, s14, v14
	v_fma_f32 v95, v59, s14, v14
	s_nop 0
	v_max3_f32 v15, v15, v94, v95
	v_fma_f32 v90, v60, s14, v14
	v_fma_f32 v91, v61, s14, v14
	s_nop 0
	v_max3_f32 v48, v15, v90, v91
	v_fma_f32 v15, v63, s14, v14
	v_fmac_f32_e32 v14, s14, v62
	s_nop 0
	v_max3_f32 v139, v48, v14, v15
; #define MFMA(a, b, c) __builtin_amdgcn_mfma_f32_32x32x16_bf16((a), (b), (c), 0, 0, 0)
; DI f32x16 zero16() { f32x16 z; for (int i = 0; i < 16; ++i) z[i] = 0.f; return z; }
; DI void attn_item(const Params& p, char* lds, int item) {
;     ...
;       for (int sub = 0; sub < 2; ++sub) {
;         const u16* kl = Kl + cur * 64 * 72 + (sub * 32 + pi) * 72 + 8 * hh;
;         S[sub] = zero16();
; #pragma unroll
;         for (int kk = 0; kk < 4; ++kk) S[sub] = MFMA(ldfrag(kl + kk * 16), Qf[kk], S[sub]);
;         const int relbase = (kc * 64 + sub * 32 + 8 * hh) - (qc * 64 + qt * 32 + l31);
;         if ((kc * 64 + sub * 32 + 31) - (qc * 64 + qt * 32) <= -128) {
;           const float b0 = biasl[0];
; #pragma unroll
;           for (int r = 0; r < 16; ++r) { const float sv = S[sub][r] * 0.18033688011112042f + b0; S[sub][r] = sv; mx = fmaxf(mx, sv); }
;         } else {
; #pragma unroll
;           for (int r = 0; r < 16; ++r) {
;             int rel = relbase + 16 * (r >> 3) + (r & 7);
;             rel = rel < -128 ? -128 : (rel > 128 ? 128 : rel);
;             const float sv = S[sub][r] * 0.18033688011112042f + biasl[rel + 128];
;             S[sub][r] = sv; mx = fmaxf(mx, sv);
;           }
;         }
.LBB0_368:
	s_or_b64 exec, exec, s[16:17]
	s_nop 5
	ds_read_b128 v[48:51], v0 offset:4608
	ds_read_b128 v[100:103], v0 offset:4640
	s_waitcnt lgkmcnt(1)
	v_mfma_f32_32x32x16_bf16 v[48:63], v[48:51], v[64:67], 0
	s_waitcnt lgkmcnt(0)
	v_mfma_f32_32x32x16_bf16 v[48:63], v[100:103], v[68:71], v[48:63]
	ds_read_b128 v[100:103], v0 offset:4672
	s_waitcnt lgkmcnt(0)
	v_mfma_f32_32x32x16_bf16 v[48:63], v[100:103], v[72:75], v[48:63]
	ds_read_b128 v[100:103], v0 offset:4704
	v_add_u32_e32 v0, 32, v98
	v_cmp_lt_i32_e32 vcc, s42, v0
	s_waitcnt lgkmcnt(0)
	v_mfma_f32_32x32x16_bf16 v[48:63], v[100:103], v[76:79], v[48:63]
	s_and_saveexec_b64 s[16:17], vcc
	s_xor_b64 s[16:17], exec, s[16:17]
	s_cbranch_execz .LBB0_370
	v_add3_u32 v0, v135, s22, 32
	v_med3_i32 v98, v0, s43, v115
	v_med3_i32 v99, v0, s48, v116
	v_med3_i32 v100, v0, s50, v117
	v_med3_i32 v101, v0, s51, v118
	v_med3_i32 v102, v0, s54, v119
	v_med3_i32 v103, v0, s55, v120
	v_med3_i32 v104, v0, s56, v121
	v_med3_i32 v105, v0, s57, v122
	v_lshl_add_u32 v98, v98, 2, 0
	v_lshl_add_u32 v99, v99, 2, 0
	v_lshl_add_u32 v100, v100, 2, 0
	v_lshl_add_u32 v101, v101, 2, 0
	v_lshl_add_u32 v102, v102, 2, 0
	v_lshl_add_u32 v103, v103, 2, 0
	v_lshl_add_u32 v104, v104, 2, 0
	v_lshl_add_u32 v105, v105, 2, 0
	ds_read_b32 v98, v98 offset:37376
	ds_read_b32 v99, v99 offset:37380
	ds_read_b32 v100, v100 offset:37384
	ds_read_b32 v101, v101 offset:37388
	ds_read_b32 v102, v102 offset:37392
	ds_read_b32 v103, v103 offset:37396
	ds_read_b32 v104, v104 offset:37400
	ds_read_b32 v105, v105 offset:37404
	s_waitcnt lgkmcnt(6)
	v_fmac_f32_e32 v98, s14, v48
	v_fmac_f32_e32 v99, s14, v49
	s_waitcnt lgkmcnt(4)
	v_fmac_f32_e32 v100, s14, v50
	v_fmac_f32_e32 v101, s14, v51
	v_max3_f32 v48, v139, v98, v99
	v_max3_f32 v48, v48, v100, v101
	s_waitcnt lgkmcnt(2)
	v_fmac_f32_e32 v102, s14, v52
	v_fmac_f32_e32 v103, s14, v53
	s_waitcnt lgkmcnt(0)
	v_fmac_f32_e32 v104, s14, v54
	v_fmac_f32_e32 v105, s14, v55
	v_max3_f32 v48, v48, v102, v103
	v_max3_f32 v108, v48, v104, v105
	v_med3_i32 v48, v0, s58, v123
	v_med3_i32 v49, v0, s59, v124
	v_med3_i32 v50, v0, s60, v125
	v_med3_i32 v51, v0, s61, v126
	v_med3_i32 v52, v0, s72, v127
	v_med3_i32 v53, v0, s73, v128
	v_med3_i32 v54, v0, s74, v129
	v_lshl_add_u32 v48, v48, 2, 0
	v_lshl_add_u32 v49, v49, 2, 0
	v_lshl_add_u32 v50, v50, 2, 0
	v_lshl_add_u32 v51, v51, 2, 0
	v_lshl_add_u32 v52, v52, 2, 0
	v_lshl_add_u32 v53, v53, 2, 0
	v_lshl_add_u32 v54, v54, 2, 0
	v_med3_i32 v0, v0, s75, v130
	v_lshl_add_u32 v0, v0, 2, 0
	ds_read_b32 v48, v48 offset:37440
	ds_read_b32 v49, v49 offset:37444
	ds_read_b32 v50, v50 offset:37448
	ds_read_b32 v51, v51 offset:37452
	ds_read_b32 v52, v52 offset:37456
	ds_read_b32 v53, v53 offset:37460
	ds_read_b32 v54, v54 offset:37464
	ds_read_b32 v55, v0 offset:37468
	s_waitcnt lgkmcnt(6)
	v_fma_f32 v106, v56, s14, v48
	v_fma_f32 v107, v57, s14, v49
	s_waitcnt lgkmcnt(2)
	v_fma_f32 v110, v60, s14, v52
	v_fma_f32 v111, v61, s14, v53
	v_max3_f32 v0, v108, v106, v107
	v_fma_f32 v108, v58, s14, v50
	v_fma_f32 v109, v59, s14, v51
	s_waitcnt lgkmcnt(0)
	v_fma_f32 v112, v62, s14, v54
	v_fma_f32 v113, v63, s14, v55
	v_max3_f32 v0, v0, v108, v109
	v_max3_f32 v0, v0, v110, v111
	v_max3_f32 v0, v0, v112, v113
.LBB0_370:
	s_andn2_saveexec_b64 s[16:17], s[16:17]
	s_cbranch_execz .LBB0_372
	ds_read_b32 v0, v1 offset:36864
	s_waitcnt lgkmcnt(0)
	s_nop 4
	v_fma_f32 v98, v48, s14, v0
	v_fma_f32 v99, v49, s14, v0
	v_fma_f32 v100, v50, s14, v0
	v_fma_f32 v101, v51, s14, v0
	v_max3_f32 v48, v139, v98, v99
	v_fma_f32 v102, v52, s14, v0
	v_fma_f32 v103, v53, s14, v0
	v_max3_f32 v48, v48, v100, v101
	v_fma_f32 v104, v54, s14, v0
	v_fma_f32 v105, v55, s14, v0
	v_max3_f32 v48, v48, v102, v103
	v_fma_f32 v106, v56, s14, v0
	v_fma_f32 v107, v57, s14, v0
	v_max3_f32 v48, v48, v104, v105
	v_max3_f32 v48, v48, v106, v107
	v_fma_f32 v108, v58, s14, v0
	v_fma_f32 v109, v59, s14, v0
	v_fma_f32 v110, v60, s14, v0
	v_fma_f32 v111, v61, s14, v0
	v_max3_f32 v48, v48, v108, v109
	v_max3_f32 v48, v48, v110, v111
	v_fma_f32 v112, v62, s14, v0
	v_fma_f32 v113, v63, s14, v0
	s_nop 0
	v_max3_f32 v0, v48, v112, v113
; #define MFMA(a, b, c) __builtin_amdgcn_mfma_f32_32x32x16_bf16((a), (b), (c), 0, 0, 0)
; DI unsigned pack2(float a, float b) { const f32x2 v = {a, b}; return __builtin_bit_cast(unsigned, __builtin_convertvector(v, bf16v2)); }
; DI void attn_item(const Params& p, char* lds, int item) {
;     ...
;       mx = fmaxf(mx, __shfl_xor(mx, 32));
;       const float mnew = fmaxf(mrun, mx);
;       const float alpha = __builtin_amdgcn_exp2f(mrun - mnew);
;       mrun = mnew;
;       float ps = 0.f;
; #pragma unroll
;       for (int sub = 0; sub < 2; ++sub)
; #pragma unroll
;         for (int r = 0; r < 16; ++r) { const float e = __builtin_amdgcn_exp2f(S[sub][r] - mnew); S[sub][r] = e; ps += e; }
;       lrun = lrun * alpha + ps;
; #pragma unroll
;       for (int r = 0; r < 16; ++r) { O[0][r] *= alpha; O[1][r] *= alpha; }
; #pragma unroll
;       for (int sub = 0; sub < 2; ++sub) {
;         bf16x8 Pf[2];
; #pragma unroll
;         for (int ks = 0; ks < 2; ++ks) {
;           union { bf16x8 v; unsigned u[4]; } cv;
;           for (int j2 = 0; j2 < 4; ++j2) cv.u[j2] = pack2(S[sub][8 * ks + 2 * j2], S[sub][8 * ks + 2 * j2 + 1]);
;           Pf[ks] = cv.v;
;         }
;         const u16* vl = Vl + cur * 64 * 72 + l31 * 72 + sub * 32 + 8 * hh;
; #pragma unroll
;         for (int dt = 0; dt < 2; ++dt)
; #pragma unroll
;           for (int ks = 0; ks < 2; ++ks) O[dt] = MFMA(ldfrag(vl + dt * 32 * 72 + 16 * ks), Pf[ks], O[dt]);
;       }
.LBB0_372:
	s_or_b64 exec, exec, s[16:17]
	s_nop 5
	v_and_b32_e32 v49, 64, v114
	v_xor_b32_e32 v48, 32, v114
	v_add_u32_e32 v49, 64, v49
	v_cmp_lt_i32_e32 vcc, v48, v49
	s_nop 1
	v_cndmask_b32_e32 v48, v114, v48, vcc
	v_lshlrev_b32_e32 v48, 2, v48
	ds_bpermute_b32 v48, v48, v0
	s_waitcnt lgkmcnt(0)
	v_max3_f32 v48, v138, v0, v48
	v_sub_f32_e32 v49, v92, v48
	v_exp_f32_e32 v49, v49
	v_sub_f32_e32 v51, v93, v48
	v_exp_f32_e32 v51, v51
	v_sub_f32_e32 v52, v88, v48
	v_exp_f32_e32 v52, v52
	v_sub_f32_e32 v53, v89, v48
	v_exp_f32_e32 v53, v53
	v_sub_f32_e32 v12, v12, v48
	v_add_f32_e32 v50, 0, v49
	v_exp_f32_e32 v54, v12
	v_add_f32_e32 v50, v51, v50
	v_add_f32_e32 v50, v52, v50
	v_add_f32_e32 v50, v53, v50
	v_sub_f32_e32 v13, v13, v48
	v_add_f32_e32 v12, v54, v50
	v_exp_f32_e32 v50, v13
	v_sub_f32_e32 v10, v10, v48
	v_exp_f32_e32 v55, v10
	v_sub_f32_e32 v11, v11, v48
	v_add_f32_e32 v12, v50, v12
	v_exp_f32_e32 v11, v11
	v_add_f32_e32 v10, v55, v12
	v_sub_f32_e32 v12, v96, v48
	v_exp_f32_e32 v56, v12
	v_sub_f32_e32 v12, v97, v48
	v_exp_f32_e32 v57, v12
	v_sub_f32_e32 v12, v94, v48
	v_exp_f32_e32 v58, v12
	v_sub_f32_e32 v12, v95, v48
	v_exp_f32_e32 v59, v12
	v_sub_f32_e32 v12, v90, v48
	v_exp_f32_e32 v60, v12
	v_sub_f32_e32 v12, v91, v48
	v_exp_f32_e32 v61, v12
	v_sub_f32_e32 v12, v14, v48
	v_exp_f32_e32 v62, v12
	v_sub_f32_e32 v12, v15, v48
	v_exp_f32_e32 v63, v12
	v_sub_f32_e32 v12, v98, v48
	v_exp_f32_e32 v88, v12
	v_sub_f32_e32 v12, v99, v48
	v_exp_f32_e32 v89, v12
	v_sub_f32_e32 v12, v100, v48
	v_exp_f32_e32 v90, v12
	v_sub_f32_e32 v12, v101, v48
	v_exp_f32_e32 v91, v12
	v_sub_f32_e32 v12, v102, v48
	v_exp_f32_e32 v92, v12
	v_sub_f32_e32 v12, v103, v48
	v_exp_f32_e32 v93, v12
	v_sub_f32_e32 v12, v104, v48
	v_exp_f32_e32 v94, v12
	v_sub_f32_e32 v12, v105, v48
	v_exp_f32_e32 v95, v12
	v_sub_f32_e32 v12, v106, v48
	v_exp_f32_e32 v96, v12
	v_sub_f32_e32 v12, v107, v48
	v_add_f32_e32 v10, v11, v10
	v_exp_f32_e32 v97, v12
	v_sub_f32_e32 v12, v108, v48
	v_add_f32_e32 v10, v56, v10
	v_exp_f32_e32 v98, v12
	v_sub_f32_e32 v12, v109, v48
	v_add_f32_e32 v10, v57, v10
	v_exp_f32_e32 v99, v12
	v_sub_f32_e32 v12, v110, v48
	v_add_f32_e32 v10, v58, v10
	v_exp_f32_e32 v100, v12
	v_sub_f32_e32 v12, v111, v48
	v_sub_f32_e32 v0, v138, v48
	v_add_f32_e32 v10, v59, v10
	v_exp_f32_e32 v101, v12
	v_sub_f32_e32 v12, v112, v48
	v_add_f32_e32 v10, v60, v10
	v_exp_f32_e32 v102, v12
	v_sub_f32_e32 v12, v113, v48
	v_exp_f32_e32 v0, v0
	v_add_u32_e32 v104, s30, v133
	v_add_f32_e32 v10, v61, v10
	v_exp_f32_e32 v103, v12
	v_cvt_pk_bf16_f32 v12, v49, v51
	v_cvt_pk_bf16_f32 v13, v52, v53
	v_cvt_pk_bf16_f32 v14, v54, v50
	v_cvt_pk_bf16_f32 v15, v55, v11
	v_cvt_pk_bf16_f32 v50, v56, v57
	v_cvt_pk_bf16_f32 v51, v58, v59
	v_cvt_pk_bf16_f32 v52, v60, v61
	ds_read_b128 v[54:57], v104 offset:18432
	ds_read_b128 v[58:61], v104 offset:18464
	v_mul_f32_e32 v46, v46, v0
	v_mul_f32_e32 v47, v47, v0
	v_mul_f32_e32 v44, v44, v0
	v_mul_f32_e32 v45, v45, v0
	v_mul_f32_e32 v42, v42, v0
	v_mul_f32_e32 v43, v43, v0
	v_mul_f32_e32 v40, v40, v0
	v_mul_f32_e32 v41, v41, v0
	v_mul_f32_e32 v38, v38, v0
	v_mul_f32_e32 v39, v39, v0
	v_mul_f32_e32 v36, v36, v0
	v_mul_f32_e32 v37, v37, v0
	v_mul_f32_e32 v34, v34, v0
	v_mul_f32_e32 v35, v35, v0
	v_mul_f32_e32 v32, v32, v0
	v_mul_f32_e32 v33, v33, v0
	v_mul_f32_e32 v30, v30, v0
	v_mul_f32_e32 v31, v31, v0
	v_mul_f32_e32 v28, v28, v0
	v_mul_f32_e32 v29, v29, v0
	s_waitcnt lgkmcnt(1)
	v_mfma_f32_32x32x16_bf16 v[32:47], v[54:57], v[12:15], v[32:47]
	ds_read_b128 v[54:57], v104 offset:23040
	v_mul_f32_e64 v26, v26, v0
	v_mul_f32_e64 v27, v27, v0
	v_mul_f32_e64 v24, v24, v0
	v_mul_f32_e64 v25, v25, v0
	v_mul_f32_e32 v22, v22, v0
	v_mul_f32_e32 v23, v23, v0
	v_mul_f32_e32 v20, v20, v0
	v_mul_f32_e32 v21, v21, v0
	v_mul_f32_e32 v18, v18, v0
	v_mul_f32_e32 v19, v19, v0
	v_mul_f32_e32 v16, v16, v0
	v_mul_f32_e32 v17, v17, v0
	v_cvt_pk_bf16_f32 v53, v62, v63
	v_add_f32_e32 v10, v62, v10
	s_waitcnt lgkmcnt(0)
	v_mfma_f32_32x32x16_bf16 v[16:31], v[54:57], v[12:15], v[16:31]
	ds_read_b128 v[12:15], v104 offset:23072
	ds_read_b128 v[54:57], v104 offset:18496
	v_add_f32_e32 v10, v63, v10
	v_add_f32_e32 v10, v88, v10
	v_add_f32_e32 v10, v89, v10
	v_add_f32_e32 v10, v90, v10
	v_add_f32_e32 v10, v91, v10
	v_mfma_f32_32x32x16_bf16 v[32:47], v[58:61], v[50:53], v[32:47]
	v_add_f32_e32 v10, v92, v10
	v_add_f32_e32 v10, v93, v10
	v_add_f32_e32 v10, v94, v10
	v_add_f32_e32 v10, v95, v10
	v_add_f32_e32 v10, v96, v10
	v_add_f32_e32 v10, v97, v10
	v_add_f32_e32 v10, v98, v10
	s_waitcnt lgkmcnt(1)
	v_mfma_f32_32x32x16_bf16 v[16:31], v[12:15], v[50:53], v[16:31]
	v_cvt_pk_bf16_f32 v12, v88, v89
	v_cvt_pk_bf16_f32 v13, v90, v91
	v_cvt_pk_bf16_f32 v14, v92, v93
	v_cvt_pk_bf16_f32 v15, v94, v95
	v_cvt_pk_bf16_f32 v50, v96, v97
	v_cvt_pk_bf16_f32 v51, v98, v99
	v_cvt_pk_bf16_f32 v52, v100, v101
	s_waitcnt lgkmcnt(0)
	v_mfma_f32_32x32x16_bf16 v[32:47], v[54:57], v[12:15], v[32:47]
	ds_read_b128 v[54:57], v104 offset:18528
	v_cvt_pk_bf16_f32 v53, v102, v103
	v_add_f32_e32 v10, v99, v10
	v_add_f32_e32 v10, v100, v10
	v_add_f32_e32 v10, v101, v10
	v_add_f32_e32 v10, v102, v10
	v_add_f32_e32 v10, v103, v10
	s_waitcnt lgkmcnt(0)
	v_mfma_f32_32x32x16_bf16 v[32:47], v[54:57], v[50:53], v[32:47]
	ds_read_b128 v[54:57], v104 offset:23104
	v_fmac_f32_e32 v10, v137, v0
	v_mov_b32_e32 v138, v48
	v_mov_b32_e32 v137, v10
	s_waitcnt lgkmcnt(0)
	v_mfma_f32_32x32x16_bf16 v[16:31], v[54:57], v[12:15], v[16:31]
	ds_read_b128 v[12:15], v104 offset:23136
	s_waitcnt lgkmcnt(0)
	v_mfma_f32_32x32x16_bf16 v[16:31], v[12:15], v[50:53], v[16:31]

; #define MFMA(a, b, c) __builtin_amdgcn_mfma_f32_32x32x16_bf16((a), (b), (c), 0, 0, 0)
; DI unsigned pack2(float a, float b) { const f32x2 v = {a, b}; return __builtin_bit_cast(unsigned, __builtin_convertvector(v, bf16v2)); }
; DI f32x16 zero16() { f32x16 z; for (int i = 0; i < 16; ++i) z[i] = 0.f; return z; }
; DI void phase_xattn(const Params& p, char* lds) {
;     ...
;       f32x16 S = zero16();
; #pragma unroll
;       for (int kk = 0; kk < 16; ++kk) S = MFMA(ldfrag(kl + kk * 16), Qf[kk], S);
;       float mx = -INFINITY;
; #pragma unroll
;       for (int r = 0; r < 16; ++r) { S[r] *= 0.09016844005556021f; mx = fmaxf(mx, S[r]); }
;       mx = fmaxf(mx, __shfl_xor(mx, 32));
;       const float mnew = fmaxf(mrun, mx), alpha = __builtin_amdgcn_exp2f(mrun - mnew);
;       mrun = mnew;
;       float ps = 0.f;
; #pragma unroll
;       for (int r = 0; r < 16; ++r) { const float e = __builtin_amdgcn_exp2f(S[r] - mnew); S[r] = e; ps += e; }
;       lrun = lrun * alpha + ps;
;       bf16x8 Pf[2];
; #pragma unroll
;       for (int ks = 0; ks < 2; ++ks) {
;         union { bf16x8 v; unsigned u[4]; } cv;
;         for (int j2 = 0; j2 < 4; ++j2) cv.u[j2] = pack2(S[8 * ks + 2 * j2], S[8 * ks + 2 * j2 + 1]);
;         Pf[ks] = cv.v;
;       }
; #pragma unroll
;       for (int dt = 0; dt < 4; ++dt) {
; #pragma unroll
;         for (int r = 0; r < 16; ++r) O[dt][r] *= alpha;
; #pragma unroll
;         for (int ks = 0; ks < 2; ++ks) O[dt] = MFMA(ldfrag(vl + dt * 32 * 40 + 16 * ks), Pf[ks], O[dt]);
;       }
.LBB0_905:
	s_and_b32 s17, s16, 1
	s_mul_i32 s6, s17, 0x4200
	v_add_u32_e32 v187, s6, v182
	ds_read_b128 v[64:67], v187
	ds_read_b128 v[188:191], v187 offset:32
	s_mul_i32 s6, s17, 0x2800
	v_add_u32_e32 v200, s6, v183
	s_and_b32 s6, s16, 7
	s_waitcnt vmcnt(15) lgkmcnt(1)
	v_mfma_f32_32x32x16_bf16 v[64:79], v[64:67], v[92:95], 0
	s_cmp_lg_u32 s6, 7
	s_waitcnt vmcnt(14) lgkmcnt(0)
	v_mfma_f32_32x32x16_bf16 v[64:79], v[188:191], v[96:99], v[64:79]
	ds_read_b128 v[188:191], v187 offset:64
	ds_read_b128 v[192:195], v187 offset:96
	s_waitcnt vmcnt(13) lgkmcnt(1)
	v_mfma_f32_32x32x16_bf16 v[64:79], v[188:191], v[100:103], v[64:79]
	s_waitcnt vmcnt(12) lgkmcnt(0)
	v_mfma_f32_32x32x16_bf16 v[64:79], v[192:195], v[104:107], v[64:79]
	ds_read_b128 v[188:191], v187 offset:128
	ds_read_b128 v[192:195], v187 offset:160
	s_waitcnt vmcnt(11) lgkmcnt(1)
	v_mfma_f32_32x32x16_bf16 v[64:79], v[188:191], v[108:111], v[64:79]
	s_waitcnt vmcnt(10) lgkmcnt(0)
	v_mfma_f32_32x32x16_bf16 v[64:79], v[192:195], v[112:115], v[64:79]
	ds_read_b128 v[188:191], v187 offset:192
	ds_read_b128 v[192:195], v187 offset:224
	s_waitcnt vmcnt(9) lgkmcnt(1)
	v_mfma_f32_32x32x16_bf16 v[64:79], v[188:191], v[116:119], v[64:79]
	s_waitcnt vmcnt(8) lgkmcnt(0)
	v_mfma_f32_32x32x16_bf16 v[64:79], v[192:195], v[120:123], v[64:79]
	ds_read_b128 v[188:191], v187 offset:256
	ds_read_b128 v[192:195], v187 offset:288
	s_waitcnt vmcnt(7) lgkmcnt(1)
	v_mfma_f32_32x32x16_bf16 v[64:79], v[188:191], v[124:127], v[64:79]
	s_waitcnt vmcnt(6) lgkmcnt(0)
	v_mfma_f32_32x32x16_bf16 v[64:79], v[192:195], v[128:131], v[64:79]
	ds_read_b128 v[188:191], v187 offset:320
	ds_read_b128 v[192:195], v187 offset:352
	s_waitcnt vmcnt(5) lgkmcnt(1)
	v_mfma_f32_32x32x16_bf16 v[64:79], v[188:191], v[132:135], v[64:79]
	s_waitcnt vmcnt(4) lgkmcnt(0)
	v_mfma_f32_32x32x16_bf16 v[64:79], v[192:195], v[136:139], v[64:79]
	ds_read_b128 v[188:191], v187 offset:384
	ds_read_b128 v[192:195], v187 offset:416
	s_waitcnt vmcnt(3) lgkmcnt(1)
	v_mfma_f32_32x32x16_bf16 v[64:79], v[188:191], v[140:143], v[64:79]
	s_waitcnt vmcnt(2) lgkmcnt(0)
	v_mfma_f32_32x32x16_bf16 v[64:79], v[192:195], v[144:147], v[64:79]
	ds_read_b128 v[188:191], v187 offset:448
	ds_read_b128 v[192:195], v187 offset:480
	s_waitcnt vmcnt(1) lgkmcnt(1)
	v_mfma_f32_32x32x16_bf16 v[64:79], v[188:191], v[148:151], v[64:79]
	ds_read_b128 v[188:191], v200 offset:33792
	ds_read_b128 v[196:199], v200 offset:33824
	s_waitcnt vmcnt(0) lgkmcnt(2)
	v_mfma_f32_32x32x16_bf16 v[64:79], v[192:195], v[152:155], v[64:79]
	s_nop 11
	v_mul_f32_e32 v187, 0x3db8aa3b, v64
	v_mul_f32_e32 v192, 0x3db8aa3b, v65
	v_mul_f32_e32 v193, 0x3db8aa3b, v66
	v_mul_f32_e32 v194, 0x3db8aa3b, v67
	v_max3_f32 v187, v187, s12, v192
	v_mul_f32_e32 v195, 0x3db8aa3b, v68
	v_mul_f32_e32 v201, 0x3db8aa3b, v69
	v_max3_f32 v187, v187, v193, v194
	v_mul_f32_e32 v202, 0x3db8aa3b, v70
	v_mul_f32_e32 v204, 0x3db8aa3b, v71
	v_max3_f32 v187, v187, v195, v201
	v_mul_f32_e32 v205, 0x3db8aa3b, v72
	v_mul_f32_e32 v206, 0x3db8aa3b, v73
	v_max3_f32 v187, v187, v202, v204
	v_mul_f32_e32 v207, 0x3db8aa3b, v74
	v_mul_f32_e32 v208, 0x3db8aa3b, v75
	v_max3_f32 v187, v187, v205, v206
	v_mul_f32_e32 v209, 0x3db8aa3b, v76
	v_mul_f32_e32 v210, 0x3db8aa3b, v77
	v_max3_f32 v187, v187, v207, v208
	v_mul_f32_e32 v211, 0x3db8aa3b, v78
	v_mul_f32_e32 v212, 0x3db8aa3b, v79
	v_max3_f32 v187, v187, v209, v210
	v_max3_f32 v187, v187, v211, v212
	ds_bpermute_b32 v201, v184, v187
	ds_read_b128 v[192:195], v200 offset:36352
	ds_read_b128 v[204:207], v200 offset:36384
	ds_read_b128 v[208:211], v200 offset:38912
	ds_read_b128 v[212:215], v200 offset:38944
	s_waitcnt lgkmcnt(4)
	v_max3_f32 v187, v186, v187, v201
	v_fma_f32 v64, v64, s2, -v187
	v_fma_f32 v65, v65, s2, -v187
	v_exp_f32_e32 v201, v64
	v_fma_f32 v66, v66, s2, -v187
	v_exp_f32_e32 v202, v65
	v_fma_f32 v67, v67, s2, -v187
	v_exp_f32_e32 v216, v66
	v_fma_f32 v68, v68, s2, -v187
	v_fma_f32 v76, v76, s2, -v187
	v_exp_f32_e32 v217, v67
	v_fma_f32 v69, v69, s2, -v187
	v_exp_f32_e32 v218, v68
	v_exp_f32_e32 v227, v76
	v_add_f32_e32 v76, 0, v201
	v_fma_f32 v70, v70, s2, -v187
	v_fma_f32 v72, v72, s2, -v187
	v_fma_f32 v73, v73, s2, -v187
	v_fma_f32 v74, v74, s2, -v187
	v_fma_f32 v75, v75, s2, -v187
	v_exp_f32_e32 v219, v69
	v_add_f32_e32 v76, v202, v76
	v_fma_f32 v71, v71, s2, -v187
	v_exp_f32_e32 v220, v70
	v_exp_f32_e32 v223, v72
	v_exp_f32_e32 v224, v73
	v_exp_f32_e32 v225, v74
	v_exp_f32_e32 v226, v75
	ds_read_b128 v[72:75], v200 offset:41472
	v_add_f32_e32 v76, v216, v76
	v_exp_f32_e32 v221, v71
	v_add_f32_e32 v76, v217, v76
	v_sub_f32_e32 v186, v186, v187
	v_add_f32_e32 v76, v218, v76
	v_exp_f32_e32 v186, v186
	v_add_f32_e32 v76, v219, v76
	v_add_f32_e32 v76, v220, v76
	v_add_f32_e32 v76, v221, v76
	v_add_f32_e32 v76, v223, v76
	v_fma_f32 v77, v77, s2, -v187
	v_fma_f32 v78, v78, s2, -v187
	v_fma_f32 v79, v79, s2, -v187
	v_cvt_pk_bf16_f32 v64, v201, v202
	v_cvt_pk_bf16_f32 v65, v216, v217
	v_cvt_pk_bf16_f32 v66, v218, v219
	v_cvt_pk_bf16_f32 v67, v220, v221
	v_mul_f32_e32 v62, v62, v186
	v_mul_f32_e32 v63, v63, v186
	v_mul_f32_e32 v60, v60, v186
	v_mul_f32_e32 v61, v61, v186
	v_mul_f32_e32 v58, v58, v186
	v_mul_f32_e32 v59, v59, v186
	v_mul_f32_e32 v56, v56, v186
	v_mul_f32_e32 v57, v57, v186
	v_mul_f32_e32 v54, v54, v186
	v_mul_f32_e32 v55, v55, v186
	v_mul_f32_e32 v52, v52, v186
	v_mul_f32_e32 v53, v53, v186
	v_mul_f32_e32 v50, v50, v186
	v_mul_f32_e32 v51, v51, v186
	v_mul_f32_e32 v48, v48, v186
	v_mul_f32_e32 v49, v49, v186
	v_add_f32_e32 v76, v224, v76
	v_mul_f32_e32 v14, v14, v186
	v_mul_f32_e32 v15, v15, v186
	v_mul_f32_e32 v12, v12, v186
	v_mul_f32_e32 v13, v13, v186
; #define MFMA(a, b, c) __builtin_amdgcn_mfma_f32_32x32x16_bf16((a), (b), (c), 0, 0, 0)
; DI unsigned pack2(float a, float b) { const f32x2 v = {a, b}; return __builtin_bit_cast(unsigned, __builtin_convertvector(v, bf16v2)); }
; DI void phase_xattn(const Params& p, char* lds) {
;     ...
;       bf16x8 Pf[2];
; #pragma unroll
;       for (int ks = 0; ks < 2; ++ks) {
;         union { bf16x8 v; unsigned u[4]; } cv;
;         for (int j2 = 0; j2 < 4; ++j2) cv.u[j2] = pack2(S[8 * ks + 2 * j2], S[8 * ks + 2 * j2 + 1]);
;         Pf[ks] = cv.v;
;       }
; #pragma unroll
;       for (int dt = 0; dt < 4; ++dt) {
; #pragma unroll
;         for (int r = 0; r < 16; ++r) O[dt][r] *= alpha;
; #pragma unroll
;         for (int ks = 0; ks < 2; ++ks) O[dt] = MFMA(ldfrag(vl + dt * 32 * 40 + 16 * ks), Pf[ks], O[dt]);
;       }
;       if (kt == 7) {
	v_mfma_f32_32x32x16_bf16 v[48:63], v[188:191], v[64:67], v[48:63]
	v_mul_f32_e64 v10, v10, v186
	v_mul_f32_e64 v11, v11, v186
	v_mul_f32_e64 v8, v8, v186
	v_mul_f32_e64 v9, v9, v186
	v_mul_f32_e64 v6, v6, v186
	v_mul_f32_e64 v7, v7, v186
	v_mul_f32_e32 v4, v4, v186
	v_mul_f32_e32 v5, v5, v186
	v_mul_f32_e32 v2, v2, v186
	v_mul_f32_e32 v3, v3, v186
	v_mul_f32_e32 v0, v0, v186
	v_mul_f32_e32 v1, v1, v186
	v_mul_f32_e32 v46, v46, v186
	v_mul_f32_e32 v47, v47, v186
	v_mul_f32_e32 v44, v44, v186
	v_mul_f32_e32 v45, v45, v186
	v_mul_f32_e32 v42, v42, v186
	v_mul_f32_e32 v43, v43, v186
	v_mul_f32_e32 v40, v40, v186
	v_mul_f32_e32 v41, v41, v186
	v_mul_f32_e32 v38, v38, v186
	v_mul_f32_e32 v39, v39, v186
	v_mul_f32_e32 v36, v36, v186
	v_mul_f32_e32 v37, v37, v186
	v_mul_f32_e32 v34, v34, v186
	v_mul_f32_e32 v35, v35, v186
	v_mul_f32_e32 v32, v32, v186
	v_mul_f32_e32 v33, v33, v186
	v_exp_f32_e32 v188, v77
	v_exp_f32_e32 v189, v78
	v_exp_f32_e32 v190, v79
	v_mul_f32_e32 v30, v30, v186
	v_mul_f32_e32 v31, v31, v186
	v_add_f32_e32 v191, v225, v76
	v_mul_f32_e32 v28, v28, v186
	v_mul_f32_e32 v29, v29, v186
	v_mul_f32_e32 v26, v26, v186
	v_mul_f32_e32 v27, v27, v186
	v_mul_f32_e32 v24, v24, v186
	v_mul_f32_e32 v25, v25, v186
	v_mul_f32_e32 v22, v22, v186
	v_mul_f32_e32 v23, v23, v186
	v_mul_f32_e32 v20, v20, v186
	v_mul_f32_e32 v21, v21, v186
	v_mul_f32_e32 v18, v18, v186
	v_mul_f32_e32 v19, v19, v186
	v_mul_f32_e32 v16, v16, v186
	v_mul_f32_e32 v17, v17, v186
	ds_read_b128 v[76:79], v200 offset:41504
	s_waitcnt lgkmcnt(5)
	v_mfma_f32_32x32x16_bf16 v[0:15], v[192:195], v[64:67], v[0:15]
	v_cvt_pk_bf16_f32 v68, v223, v224
	v_cvt_pk_bf16_f32 v69, v225, v226
	v_cvt_pk_bf16_f32 v70, v227, v188
	v_cvt_pk_bf16_f32 v71, v189, v190
	s_waitcnt lgkmcnt(3)
	v_mfma_f32_32x32x16_bf16 v[32:47], v[208:211], v[64:67], v[32:47]
	s_waitcnt lgkmcnt(1)
	v_mfma_f32_32x32x16_bf16 v[16:31], v[72:75], v[64:67], v[16:31]
	v_add_f32_e32 v64, v226, v191
	v_add_f32_e32 v64, v227, v64
	v_add_f32_e32 v64, v188, v64
	v_add_f32_e32 v64, v189, v64
	v_add_f32_e32 v64, v190, v64
	v_fmac_f32_e32 v64, v185, v186
	v_mfma_f32_32x32x16_bf16 v[48:63], v[196:199], v[68:71], v[48:63]
	v_mfma_f32_32x32x16_bf16 v[0:15], v[204:207], v[68:71], v[0:15]
	v_mfma_f32_32x32x16_bf16 v[32:47], v[212:215], v[68:71], v[32:47]
	s_waitcnt lgkmcnt(0)
	v_mfma_f32_32x32x16_bf16 v[16:31], v[76:79], v[68:71], v[16:31]
	s_cbranch_scc1 .LBB0_907
; DI unsigned pack2(float a, float b) { const f32x2 v = {a, b}; return __builtin_bit_cast(unsigned, __builtin_convertvector(v, bf16v2)); }
; DI f32x16 zero16() { f32x16 z; for (int i = 0; i < 16; ++i) z[i] = 0.f; return z; }
; DI void phase_xattn(const Params& p, char* lds) {
;     ...
;       if (kt == 7) {
;         const float inv = __builtin_amdgcn_rcpf(lrun + __shfl_xor(lrun, 32));
; #pragma unroll
;         for (int dt = 0; dt < 4; ++dt) {
; #pragma unroll
;           for (int g = 0; g < 4; ++g) {
;             uint2 o; o.x = pack2(O[dt][4 * g] * inv, O[dt][4 * g + 1] * inv); o.y = pack2(O[dt][4 * g + 2] * inv, O[dt][4 * g + 3] * inv);
;             *(uint2*)(XO + (q0 + l31) * 1024 + h * 256 + dh * 128 + dt * 32 + 8 * g + 4 * hh) = o;
;           }
;           O[dt] = zero16();
;         }
;         mrun = -INFINITY; lrun = 0.f;
;       }
	ds_bpermute_b32 v65, v184, v64
	s_and_b32 s6, s15, 0x80
	s_lshl_b32 s6, s6, 1
	v_lshl_add_u64 v[66:67], v[180:181], 0, s[6:7]
	v_mov_b32_e32 v187, 0xff800000
	s_waitcnt lgkmcnt(0)
	v_add_f32_e32 v64, v64, v65
	v_rcp_f32_e32 v64, v64
	s_nop 0
	v_mul_f32_e32 v0, v0, v64
	v_mul_f32_e32 v1, v1, v64
	v_mul_f32_e32 v2, v2, v64
	v_mul_f32_e32 v3, v3, v64
	v_cvt_pk_bf16_f32 v0, v0, v1
	v_cvt_pk_bf16_f32 v1, v2, v3
	global_store_dwordx2 v[66:67], v[0:1], off offset:64
	v_mul_f32_e32 v0, v4, v64
	v_mul_f32_e32 v1, v5, v64
	v_mul_f32_e32 v2, v6, v64
	v_mul_f32_e32 v3, v7, v64
	v_cvt_pk_bf16_f32 v0, v0, v1
	v_cvt_pk_bf16_f32 v1, v2, v3
	global_store_dwordx2 v[66:67], v[0:1], off offset:80
	v_mul_f32_e32 v0, v8, v64
	v_mul_f32_e32 v1, v9, v64
	v_mul_f32_e32 v2, v10, v64
	v_mul_f32_e32 v3, v11, v64
	v_cvt_pk_bf16_f32 v0, v0, v1
	v_cvt_pk_bf16_f32 v1, v2, v3
	global_store_dwordx2 v[66:67], v[0:1], off offset:96
	v_mul_f32_e32 v0, v12, v64
	v_mul_f32_e32 v1, v13, v64
	v_mul_f32_e32 v2, v14, v64
	v_mul_f32_e32 v3, v15, v64
	v_cvt_pk_bf16_f32 v0, v0, v1
	v_cvt_pk_bf16_f32 v1, v2, v3
	global_store_dwordx2 v[66:67], v[0:1], off offset:112
	v_mul_f32_e32 v0, v32, v64
	v_mul_f32_e32 v1, v33, v64
	v_mul_f32_e32 v2, v34, v64
	v_mul_f32_e32 v3, v35, v64
	v_cvt_pk_bf16_f32 v0, v0, v1
	v_cvt_pk_bf16_f32 v1, v2, v3
	global_store_dwordx2 v[66:67], v[0:1], off offset:128
	v_mul_f32_e32 v0, v36, v64
	v_mul_f32_e32 v1, v37, v64
	v_mul_f32_e32 v2, v38, v64
	v_mul_f32_e32 v3, v39, v64
	v_cvt_pk_bf16_f32 v0, v0, v1
	v_cvt_pk_bf16_f32 v1, v2, v3
	global_store_dwordx2 v[66:67], v[0:1], off offset:144
	v_mul_f32_e32 v0, v40, v64
	v_mul_f32_e32 v1, v41, v64
	v_mul_f32_e32 v2, v42, v64
	v_mul_f32_e32 v3, v43, v64
	v_cvt_pk_bf16_f32 v0, v0, v1
	v_cvt_pk_bf16_f32 v1, v2, v3
	global_store_dwordx2 v[66:67], v[0:1], off offset:160
	v_mul_f32_e32 v0, v44, v64
	v_mul_f32_e32 v1, v45, v64
	v_mul_f32_e32 v2, v46, v64
	v_mul_f32_e32 v3, v47, v64
	v_cvt_pk_bf16_f32 v0, v0, v1
	v_cvt_pk_bf16_f32 v1, v2, v3
	v_mul_f32_e32 v48, v48, v64
	v_mul_f32_e32 v49, v49, v64
	v_mul_f32_e32 v50, v50, v64
	v_mul_f32_e32 v51, v51, v64
	global_store_dwordx2 v[66:67], v[0:1], off offset:176
	v_mul_f32_e32 v0, v16, v64
	v_mul_f32_e32 v1, v17, v64
	v_mul_f32_e32 v2, v18, v64
	v_mul_f32_e32 v3, v19, v64
	v_cvt_pk_bf16_f32 v48, v48, v49
	v_cvt_pk_bf16_f32 v49, v50, v51
	v_cvt_pk_bf16_f32 v0, v0, v1
	v_cvt_pk_bf16_f32 v1, v2, v3
	v_mul_f32_e32 v52, v52, v64
	v_mul_f32_e32 v53, v53, v64
	global_store_dwordx2 v[66:67], v[48:49], off
	v_mul_f32_e32 v48, v54, v64
	v_mul_f32_e32 v49, v55, v64
	global_store_dwordx2 v[66:67], v[0:1], off offset:192
	v_mul_f32_e32 v0, v20, v64
	v_mul_f32_e32 v1, v21, v64
	v_mul_f32_e32 v2, v22, v64
	v_mul_f32_e32 v3, v23, v64
	v_cvt_pk_bf16_f32 v50, v52, v53
	v_cvt_pk_bf16_f32 v51, v48, v49
	v_cvt_pk_bf16_f32 v0, v0, v1
	v_cvt_pk_bf16_f32 v1, v2, v3
	global_store_dwordx2 v[66:67], v[50:51], off offset:16
	v_mul_f32_e32 v48, v56, v64
	v_mul_f32_e32 v49, v57, v64
	v_mul_f32_e32 v50, v58, v64
	v_mul_f32_e32 v51, v59, v64
	global_store_dwordx2 v[66:67], v[0:1], off offset:208
	v_mul_f32_e32 v0, v24, v64
	v_mul_f32_e32 v1, v25, v64
	v_mul_f32_e32 v2, v26, v64
	v_mul_f32_e32 v3, v27, v64
	v_cvt_pk_bf16_f32 v48, v48, v49
	v_cvt_pk_bf16_f32 v49, v50, v51
	v_cvt_pk_bf16_f32 v0, v0, v1
	v_cvt_pk_bf16_f32 v1, v2, v3
	global_store_dwordx2 v[66:67], v[48:49], off offset:32
	v_mul_f32_e32 v48, v60, v64
	v_mul_f32_e32 v49, v61, v64
	v_mul_f32_e32 v50, v62, v64
	v_mul_f32_e32 v51, v63, v64
	global_store_dwordx2 v[66:67], v[0:1], off offset:224
	v_mul_f32_e32 v0, v28, v64
	v_mul_f32_e32 v1, v29, v64
	v_mul_f32_e32 v2, v30, v64
	v_mul_f32_e32 v3, v31, v64
	v_cvt_pk_bf16_f32 v48, v48, v49
	v_cvt_pk_bf16_f32 v49, v50, v51
	v_cvt_pk_bf16_f32 v0, v0, v1
	v_cvt_pk_bf16_f32 v1, v2, v3
	v_mov_b32_e32 v64, 0
	global_store_dwordx2 v[66:67], v[48:49], off offset:48
	global_store_dwordx2 v[66:67], v[0:1], off offset:240
	v_mov_b32_e32 v0, 0
	v_mov_b32_e32 v1, v64
	v_mov_b32_e32 v2, v64
	v_mov_b32_e32 v3, v64
	v_mov_b32_e32 v4, v64
	v_mov_b32_e32 v5, v64
	v_mov_b32_e32 v6, v64
	v_mov_b32_e32 v7, v64
	v_mov_b32_e32 v8, v64
	v_mov_b32_e32 v9, v64
	v_mov_b32_e32 v10, v64
	v_mov_b32_e32 v11, v64
	v_mov_b32_e32 v12, v64
	v_mov_b32_e32 v13, v64
	v_mov_b32_e32 v14, v64
	v_mov_b32_e32 v15, v64
	v_mov_b32_e32 v48, 0
	v_mov_b32_e32 v49, v64
	v_mov_b32_e32 v50, v64
	v_mov_b32_e32 v51, v64
	v_mov_b32_e32 v52, v64
	v_mov_b32_e32 v53, v64
	v_mov_b32_e32 v54, v64
	v_mov_b32_e32 v55, v64
	v_mov_b32_e32 v56, v64
	v_mov_b32_e32 v57, v64
	v_mov_b32_e32 v58, v64
	v_mov_b32_e32 v59, v64
	v_mov_b32_e32 v60, v64
	v_mov_b32_e32 v61, v64
	v_mov_b32_e32 v62, v64
	v_mov_b32_e32 v63, v64
	v_mov_b32_e32 v32, 0
	v_mov_b32_e32 v33, v64
	v_mov_b32_e32 v34, v64
	v_mov_b32_e32 v35, v64
	v_mov_b32_e32 v36, v64
	v_mov_b32_e32 v37, v64
	v_mov_b32_e32 v38, v64
	v_mov_b32_e32 v39, v64
	v_mov_b32_e32 v40, v64
	v_mov_b32_e32 v41, v64
	v_mov_b32_e32 v42, v64
	v_mov_b32_e32 v43, v64
	v_mov_b32_e32 v44, v64
	v_mov_b32_e32 v45, v64
	v_mov_b32_e32 v46, v64
	v_mov_b32_e32 v47, v64
	v_mov_b32_e32 v16, 0
	v_mov_b32_e32 v17, v64
	v_mov_b32_e32 v18, v64
	v_mov_b32_e32 v19, v64
	v_mov_b32_e32 v20, v64
	v_mov_b32_e32 v21, v64
	v_mov_b32_e32 v22, v64
	v_mov_b32_e32 v23, v64
	v_mov_b32_e32 v24, v64
	v_mov_b32_e32 v25, v64
	v_mov_b32_e32 v26, v64
	v_mov_b32_e32 v27, v64
	v_mov_b32_e32 v28, v64
	v_mov_b32_e32 v29, v64
	v_mov_b32_e32 v30, v64
	v_mov_b32_e32 v31, v64
